# MLA tile loop: next tile's LDS stash addresses and global address increments computed in the PV MFMAs' shadow; the tail only waits and writes
# speedup vs baseline: 1.0086x; 1.0015x over previous
.LBB0_785:
	v_exp_f32_e32 v84, v84
	v_exp_f32_e32 v85, v85
	v_exp_f32_e32 v86, v86
	v_exp_f32_e32 v87, v87
	v_exp_f32_e32 v88, v88
	v_exp_f32_e32 v89, v89
	v_exp_f32_e32 v90, v90
	v_exp_f32_e32 v91, v91
	v_exp_f32_e32 v92, v92
	v_exp_f32_e32 v93, v93
	v_cvt_pk_bf16_f32 v238, v84, v85
	v_cvt_pk_bf16_f32 v239, v86, v87
	v_exp_f32_e32 v94, v94
	v_exp_f32_e32 v95, v95
	v_cvt_pk_bf16_f32 v240, v88, v89
	v_cvt_pk_bf16_f32 v241, v90, v91
	v_exp_f32_e32 v96, v96
	v_exp_f32_e32 v97, v97
	v_pk_add_f32 v[4:5], v[84:85], 0 op_sel_hi:[1,0]
	s_waitcnt lgkmcnt(0)
	v_mfma_f32_32x32x16_bf16 v[68:83], v[190:193], v[238:241], v[68:83]
	v_exp_f32_e32 v98, v98
	v_exp_f32_e32 v99, v99
	v_pk_add_f32 v[4:5], v[86:87], v[4:5]
	v_mfma_f32_32x32x16_bf16 v[52:67], v[222:225], v[238:241], v[52:67]
	v_cvt_pk_bf16_f32 v248, v92, v93
	v_cvt_pk_bf16_f32 v249, v94, v95
	v_cvt_pk_bf16_f32 v250, v96, v97
	v_pk_add_f32 v[4:5], v[88:89], v[4:5]
	v_cvt_pk_bf16_f32 v251, v98, v99
	v_pk_add_f32 v[4:5], v[90:91], v[4:5]
	v_pk_add_f32 v[4:5], v[92:93], v[4:5]
	v_mfma_f32_32x32x16_bf16 v[68:83], v[194:197], v[248:251], v[68:83]
	v_pk_add_f32 v[4:5], v[94:95], v[4:5]
	v_mfma_f32_32x32x16_bf16 v[52:67], v[226:229], v[248:251], v[52:67]
	s_bitcmp1_b32 s49, 0
	s_cselect_b32 s0, 0x5800, 0
	s_add_i32 s34, s0, 0
	v_add3_u32 v6, s34, v198, v142
	v_add3_u32 v7, s34, v200, v202
	v_add_u32_e32 v8, s34, v203
	s_mov_b64 s[30:31], 0x60000
	v_add3_u32 v8, v8, v205, v207
	v_lshl_add_u64 v[184:185], v[184:185], 0, s[30:31]
	s_mov_b64 s[30:31], 0x80
	v_add_u32_e32 v8, 0x3000, v8
	v_lshl_add_u64 v[186:187], v[186:187], 0, s[30:31]
	s_mov_b64 s[30:31], 0x10000
	v_lshl_add_u64 v[188:189], v[188:189], 0, s[30:31]
	v_pk_add_f32 v[4:5], v[96:97], v[4:5]
	v_pk_add_f32 v[4:5], v[98:99], v[4:5]
	s_and_b64 vcc, exec, s[80:81]
	s_cbranch_vccnz .LBB0_789
	s_branch .Lmla_s1
.Lmla_specA:
	s_waitcnt lgkmcnt(0)
	v_pk_add_f32 v[4:5], v[238:239], 0 op_sel_hi:[1,0]
	v_cvt_pk_bf16_f32 v238, v238, v239
	v_pk_add_f32 v[4:5], v[240:241], v[4:5]
	v_cvt_pk_bf16_f32 v239, v240, v241
	v_pk_add_f32 v[4:5], v[242:243], v[4:5]
	v_cvt_pk_bf16_f32 v240, v242, v243
	v_pk_add_f32 v[4:5], v[244:245], v[4:5]
	v_cvt_pk_bf16_f32 v241, v244, v245
	v_pk_add_f32 v[4:5], v[248:249], v[4:5]
	v_cvt_pk_bf16_f32 v248, v248, v249
	v_mfma_f32_32x32x16_bf16 v[68:83], v[190:193], v[238:241], v[68:83]
	v_pk_add_f32 v[4:5], v[250:251], v[4:5]
	v_cvt_pk_bf16_f32 v249, v250, v251
	v_mfma_f32_32x32x16_bf16 v[52:67], v[222:225], v[238:241], v[52:67]
	v_pk_add_f32 v[4:5], v[252:253], v[4:5]
	v_cvt_pk_bf16_f32 v250, v252, v253
	v_pk_add_f32 v[4:5], v[254:255], v[4:5]
	v_cvt_pk_bf16_f32 v251, v254, v255
	v_exp_f32_e32 v34, v34
	v_exp_f32_e32 v35, v35
	v_mfma_f32_32x32x16_bf16 v[68:83], v[194:197], v[248:251], v[68:83]
	v_exp_f32_e32 v36, v36
	v_exp_f32_e32 v37, v37
	v_mfma_f32_32x32x16_bf16 v[52:67], v[226:229], v[248:251], v[52:67]
	s_bitcmp1_b32 s49, 0
	s_cselect_b32 s0, 0x5800, 0
	s_add_i32 s34, s0, 0
	v_add3_u32 v6, s34, v198, v142
	v_add3_u32 v7, s34, v200, v202
	v_add_u32_e32 v8, s34, v203
	s_mov_b64 s[30:31], 0x60000
	v_add3_u32 v8, v8, v205, v207
	v_lshl_add_u64 v[184:185], v[184:185], 0, s[30:31]
	s_mov_b64 s[30:31], 0x80
	v_add_u32_e32 v8, 0x3000, v8
	v_lshl_add_u64 v[186:187], v[186:187], 0, s[30:31]
	s_mov_b64 s[30:31], 0x10000
	v_lshl_add_u64 v[188:189], v[188:189], 0, s[30:31]
	s_branch .Lmla_s1b

.LBB0_789:
	v_add_f32_e32 v16, v4, v5
	v_add_f32_e32 v183, v183, v16
	s_waitcnt vmcnt(1)
	ds_write_b128 v6, v[136:139]
	s_and_saveexec_b64 s[0:1], s[2:3]
	ds_write_b128 v7, v[128:131] offset:128
	s_or_b64 exec, exec, s[0:1]
	s_waitcnt vmcnt(0)
	ds_write2_b64 v8, v[132:133], v[134:135] offset0:128 offset1:130
	s_branch .Lmla_tail
.LBB0_790:
	s_bitcmp1_b32 s49, 0
	s_cselect_b32 s0, 0x5800, 0
	s_add_i32 s34, s0, 0
	v_add3_u32 v16, s34, v198, v142
	s_waitcnt vmcnt(1)
	ds_write_b128 v16, v[136:139]
	s_and_saveexec_b64 s[0:1], s[2:3]
	v_add3_u32 v16, s34, v200, v202
	ds_write_b128 v16, v[128:131] offset:128
	s_or_b64 exec, exec, s[0:1]
	s_mov_b64 s[30:31], 0x60000
	v_add_u32_e32 v16, s34, v203
	v_lshl_add_u64 v[184:185], v[184:185], 0, s[30:31]
	s_mov_b64 s[30:31], 0x80
	v_add3_u32 v16, v16, v205, v207
	v_lshl_add_u64 v[186:187], v[186:187], 0, s[30:31]
	s_mov_b64 s[30:31], 0x10000
	v_add_u32_e32 v16, 0x3000, v16
	v_lshl_add_u64 v[188:189], v[188:189], 0, s[30:31]
	s_waitcnt vmcnt(0)
	ds_write2_b64 v16, v[132:133], v[134:135] offset0:128 offset1:130
.Lmla_tail:
	s_add_i32 s48, s48, 2
	s_add_i32 s0, s49, 1
	s_cmp_lg_u32 s24, s48
	s_waitcnt lgkmcnt(0)
	s_barrier
	s_cbranch_scc0 .LBB0_794
	s_mov_b32 s49, s0
	global_load_dwordx4 v[136:139], v[188:189], off
	s_and_saveexec_b64 s[0:1], s[2:3]
	s_cbranch_execnz .LBB0_766
	s_branch .LBB0_767
